# phase 0: weight-conversion tiles rebalanced: the 384 workgroups that also compute an adaLN tile take 4 tiles each, the other 128 take the rest
# speedup vs baseline: 1.0052x; 1.0052x over previous
.LBB0_514:
	v_mov_b32_e32 v2, v0
	s_mov_b32 s13, s2
	s_cmpk_gt_i32 s13, 0xbcf
	s_cbranch_scc1 .LBB0_7
	v_readlane_b32 s0, v252, 2
	v_readlane_b32 s1, v252, 3
	s_load_dword s0, s[0:1], 0x10
	v_lshlrev_b32_e32 v3, 1, v2
	v_add_u32_e32 v23, 0x100, v2
	v_add_u32_e32 v25, 0x200, v2
	v_add_u32_e32 v27, 0x300, v2
	s_waitcnt lgkmcnt(0)
	s_lshr_b32 s0, s0, 16
	s_cmp_lg_u32 s0, 0
	v_add_u32_e32 v29, 0x400, v2
	v_add_u32_e32 v31, 0x500, v2
	v_add_u32_e32 v33, 0x600, v2
	v_add_u32_e32 v35, 0x700, v2
	v_add_u32_e32 v13, 0x800, v2
	v_add_u32_e32 v14, 0x900, v2
	v_add_u32_e32 v15, 0xa00, v2
	v_add_u32_e32 v16, 0xb00, v2
	v_add_u32_e32 v17, 0xc00, v2
	v_add_u32_e32 v18, 0xd00, v2
	v_add_u32_e32 v19, 0xe00, v2
	v_add_u32_e32 v20, 0xf00, v2
	v_and_b32_e32 v4, 63, v2
	v_and_b32_e32 v54, 62, v3
	s_cselect_b64 s[0:1], -1, 0
	v_ashrrev_i32_e32 v5, 6, v2
	v_ashrrev_i32_e32 v6, 6, v23
	v_ashrrev_i32_e32 v7, 6, v25
	v_ashrrev_i32_e32 v8, 6, v27
	v_ashrrev_i32_e32 v9, 6, v29
	v_ashrrev_i32_e32 v10, 6, v31
	v_ashrrev_i32_e32 v11, 6, v33
	v_ashrrev_i32_e32 v12, 6, v35
	v_ashrrev_i32_e32 v13, 6, v13
	v_ashrrev_i32_e32 v14, 6, v14
	v_ashrrev_i32_e32 v15, 6, v15
	v_ashrrev_i32_e32 v16, 6, v16
	v_ashrrev_i32_e32 v17, 6, v17
	v_ashrrev_i32_e32 v18, 6, v18
	v_ashrrev_i32_e32 v19, 6, v19
	v_ashrrev_i32_e32 v20, 6, v20
	v_lshl_add_u32 v52, v4, 2, 0
	s_cmp_lg_u64 s[0:1], 0
	v_mad_u32_u24 v3, v54, s85, 0
	v_mul_lo_u32 v37, v5, s85
	v_mul_lo_u32 v38, v6, s85
	v_mul_lo_u32 v39, v7, s85
	v_mul_lo_u32 v40, v8, s85
	v_mul_lo_u32 v41, v9, s85
	v_mul_lo_u32 v42, v10, s85
	v_mul_lo_u32 v43, v11, s85
	v_mul_lo_u32 v44, v12, s85
	v_mul_lo_u32 v45, v13, s85
	v_mul_lo_u32 v46, v14, s85
	v_mul_lo_u32 v47, v15, s85
	v_mul_lo_u32 v48, v16, s85
	v_mul_lo_u32 v49, v17, s85
	v_mul_lo_u32 v50, v18, s85
	v_mul_lo_u32 v51, v19, s85
	v_mul_lo_u32 v53, v20, s85
	v_ashrrev_i32_e32 v21, 5, v2
	v_ashrrev_i32_e32 v23, 5, v23
	v_ashrrev_i32_e32 v25, 5, v25
	v_ashrrev_i32_e32 v27, 5, v27
	v_ashrrev_i32_e32 v29, 5, v29
	v_ashrrev_i32_e32 v31, 5, v31
	v_ashrrev_i32_e32 v33, 5, v33
	v_ashrrev_i32_e32 v35, 5, v35
	s_addc_u32 s16, s10, 0
	v_lshl_add_u32 v22, v21, 2, v3
	v_lshl_add_u32 v24, v23, 2, v3
	v_lshl_add_u32 v26, v25, 2, v3
	v_lshl_add_u32 v28, v27, 2, v3
	v_lshl_add_u32 v30, v29, 2, v3
	v_lshl_add_u32 v32, v31, 2, v3
	v_lshl_add_u32 v34, v33, 2, v3
	v_lshl_add_u32 v36, v35, 2, v3
	v_add_u32_e32 v37, v52, v37
	v_add_u32_e32 v38, v52, v38
	v_add_u32_e32 v39, v52, v39
	v_add_u32_e32 v40, v52, v40
	v_add_u32_e32 v41, v52, v41
	v_add_u32_e32 v42, v52, v42
	v_add_u32_e32 v43, v52, v43
	v_add_u32_e32 v44, v52, v44
	v_add_u32_e32 v45, v52, v45
	v_add_u32_e32 v46, v52, v46
	v_add_u32_e32 v47, v52, v47
	v_add_u32_e32 v48, v52, v48
	v_add_u32_e32 v49, v52, v49
	v_add_u32_e32 v50, v52, v50
	v_add_u32_e32 v51, v52, v51
	v_add_u32_e32 v52, v52, v53
	v_lshlrev_b32_e32 v130, 1, v54
	s_cmp_eq_u32 s16, 0x200
	s_cbranch_scc0 .Lw0_keep
	s_cmp_lt_u32 s2, 0x180
	s_cbranch_scc0 .Lw0_hi
	s_movk_i32 s16, 0x180
	s_movk_i32 s100, 0x600
	s_branch .Lw0_set
.Lw0_hi:
	s_add_u32 s13, s2, 0x480
	s_movk_i32 s16, 0x80
	s_movk_i32 s100, 0xbd0
	s_branch .Lw0_set
.Lw0_keep:
	s_movk_i32 s100, 0xbd0

.LBB0_516:
	s_or_b64 exec, exec, s[4:5]
	s_add_i32 s13, s13, s16
	s_cmp_ge_i32 s13, s100
	s_cbranch_scc1 .LBB0_7
